# GLA consumer waves also at raised static priority (on top of delta consumer priority and the balanced version)
# baseline (speedup 1.0000x reference)
; #define LAS __attribute__((address_space(3)))
; __device__ __forceinline__ float quad_sum(float v) { v += dppf<0xB1>(v); v += dppf<0x4E>(v); return v; }
; __device__ __forceinline__ void gla_unit(const Params& P, LAS unsigned char* lds, int li, bool sample, int b, int h, const int tid) {
;     ...
;         } else if (j >= 1 && j <= NC) {
;             LAS float* qs = (LAS float*)(lds + ((j - 1) & 1) * SET); LAS float* ks = qs + 1024; LAS float* gs = qs + 2048; LAS float* vs = qs + 3072; LAS float* os = qs + 3072 + 2048;
;             const int ntok = min(MX_CH, L - (j - 1) * MX_CH);
;             f32x4 kk[2], qq[2], gg[2]; float ve;
; #pragma unroll
;             for (int i = 0; i < 2; ++i) { kk[i] = *(const LAS f32x4*)(ks + 8 * dq + 4 * i); qq[i] = *(const LAS f32x4*)(qs + 8 * dq + 4 * i); gg[i] = *(const LAS f32x4*)(gs + 8 * dq + 4 * i); }
;             ve = vs[e];
;             for (int tok = 0; tok < ntok; ++tok) {
;                 const int tn = min(tok + 1, ntok - 1);
;                 f32x4 kn[2], qn[2], gn[2];
; #pragma unroll
;                 for (int i = 0; i < 2; ++i) { kn[i] = *(const LAS f32x4*)(ks + tn * 32 + 8 * dq + 4 * i); qn[i] = *(const LAS f32x4*)(qs + tn * 32 + 8 * dq + 4 * i); gn[i] = *(const LAS f32x4*)(gs + tn * 32 + 8 * dq + 4 * i); }
;                 const float vn = vs[tn * 64 + e];
;                 const f32x2 v2 = (f32x2){ve, ve};
;                 f32x2 oa[2];
; #pragma unroll
;                 for (int i = 0; i < 2; ++i) {
;                     S[2 * i] = S[2 * i] * (f32x2){gg[i][0], gg[i][1]} + (f32x2){kk[i][0], kk[i][1]} * v2; S[2 * i + 1] = S[2 * i + 1] * (f32x2){gg[i][2], gg[i][3]} + (f32x2){kk[i][2], kk[i][3]} * v2;
;                     oa[i] = (f32x2){qq[i][0], qq[i][1]} * S[2 * i] + (f32x2){qq[i][2], qq[i][3]} * S[2 * i + 1];
;                 }
;                 const f32x2 os2 = oa[0] + oa[1];
;                 const float o = quad_sum(os2[0] + os2[1]);
;                 if (dq == 0) os[tok * 64 + e] = o;
.LBB0_253:
	s_add_i32 s0, s13, -1
	s_cmpk_gt_u32 s0, 0x7f
	v_mov_b32_e32 v31, v71
	v_mov_b32_e32 v30, v70
	v_mov_b32_e32 v33, v69
	v_mov_b32_e32 v32, v68
	v_mov_b32_e32 v35, v67
	v_mov_b32_e32 v34, v66
	v_mov_b32_e32 v37, v65
	v_mov_b32_e32 v36, v40
	s_cbranch_scc1 .LBB0_258
	s_setprio 1
	s_bitcmp1_b32 s0, 0
	s_cselect_b32 s0, 0x7000, 0
	s_add_i32 s1, s0, 0
	v_lshl_add_u32 v120, v60, 2, s1
	v_lshl_add_u32 v121, v58, 2, s1
	s_waitcnt vmcnt(0)
	s_mov_b64 s[0:1], exec
	ds_read_b128 v[80:83], v120 offset:4096
	ds_read_b128 v[84:87], v120 offset:4112
	ds_read_b32 v112, v121 offset:12288
	ds_read_b128 v[16:19], v120 offset:8192
	ds_read_b128 v[20:23], v120 offset:8208
	ds_read_b128 v[88:91], v120 offset:4224
	ds_read_b128 v[92:95], v120 offset:4240
	ds_read_b32 v114, v121 offset:12544
	ds_read_b128 v[72:75], v120 offset:8320
	ds_read_b128 v[76:79], v120 offset:8336
	ds_read_b128 v[0:3], v120 offset:0
	ds_read_b128 v[4:7], v120 offset:16
	ds_read_b128 v[8:11], v120 offset:128
	ds_read_b128 v[12:15], v120 offset:144
	s_waitcnt lgkmcnt(11)
	v_pk_mul_f32 v[96:97], v[112:113], v[80:81] op_sel_hi:[0,1]
	v_pk_mul_f32 v[98:99], v[112:113], v[82:83] op_sel_hi:[0,1]
	v_pk_mul_f32 v[100:101], v[112:113], v[84:85] op_sel_hi:[0,1]
	v_pk_mul_f32 v[102:103], v[112:113], v[86:87] op_sel_hi:[0,1]
	ds_read_b128 v[80:83], v120 offset:4352
	ds_read_b128 v[84:87], v120 offset:4368
	ds_read_b32 v112, v121 offset:12800
	s_waitcnt lgkmcnt(9)
	v_pk_fma_f32 v[36:37], v[16:17], v[36:37], v[96:97]
	v_pk_fma_f32 v[34:35], v[18:19], v[34:35], v[98:99]
	v_pk_fma_f32 v[32:33], v[20:21], v[32:33], v[100:101]
	v_pk_fma_f32 v[30:31], v[22:23], v[30:31], v[102:103]
	ds_read_b128 v[16:19], v120 offset:8448
	ds_read_b128 v[20:23], v120 offset:8464
	v_pk_mul_f32 v[104:105], v[114:115], v[88:89] op_sel_hi:[0,1]
	v_pk_mul_f32 v[106:107], v[114:115], v[90:91] op_sel_hi:[0,1]
	v_pk_mul_f32 v[108:109], v[114:115], v[92:93] op_sel_hi:[0,1]
	v_pk_mul_f32 v[110:111], v[114:115], v[94:95] op_sel_hi:[0,1]
	ds_read_b128 v[88:91], v120 offset:4480
	ds_read_b128 v[92:95], v120 offset:4496
	ds_read_b32 v114, v121 offset:13056
	s_waitcnt lgkmcnt(5)
	v_pk_mul_f32 v[116:117], v[0:1], v[36:37]
	v_pk_fma_f32 v[36:37], v[72:73], v[36:37], v[104:105]
	v_pk_mul_f32 v[118:119], v[2:3], v[34:35]
	v_pk_fma_f32 v[34:35], v[74:75], v[34:35], v[106:107]
	v_pk_fma_f32 v[116:117], v[4:5], v[32:33], v[116:117]
	v_pk_fma_f32 v[32:33], v[76:77], v[32:33], v[108:109]
	v_pk_fma_f32 v[118:119], v[6:7], v[30:31], v[118:119]
	v_pk_fma_f32 v[30:31], v[78:79], v[30:31], v[110:111]
	ds_read_b128 v[0:3], v120 offset:256
	ds_read_b128 v[4:7], v120 offset:272
	ds_read_b128 v[72:75], v120 offset:8576
	ds_read_b128 v[76:79], v120 offset:8592
	v_pk_add_f32 v[116:117], v[116:117], v[118:119]
	v_pk_mul_f32 v[96:97], v[112:113], v[80:81] op_sel_hi:[0,1]
	v_pk_mul_f32 v[98:99], v[112:113], v[82:83] op_sel_hi:[0,1]
	v_add_f32_e32 v116, v116, v117
	v_pk_mul_f32 v[100:101], v[112:113], v[84:85] op_sel_hi:[0,1]
	v_pk_mul_f32 v[102:103], v[112:113], v[86:87] op_sel_hi:[0,1]
	v_add_f32_dpp v116, v116, v116 quad_perm:[1,0,3,2] row_mask:0xf bank_mask:0xf bound_ctrl:1
	ds_read_b128 v[80:83], v120 offset:4608
	ds_read_b128 v[84:87], v120 offset:4624
	ds_read_b32 v112, v121 offset:13312
	v_add_f32_dpp v116, v116, v116 quad_perm:[2,3,0,1] row_mask:0xf bank_mask:0xf bound_ctrl:1
	s_mov_b64 exec, s[38:39]
	ds_write_b32 v121, v116 offset:20480
	s_mov_b64 exec, s[0:1]
	s_waitcnt lgkmcnt(8)
	v_pk_mul_f32 v[116:117], v[8:9], v[36:37]
	v_pk_fma_f32 v[36:37], v[16:17], v[36:37], v[96:97]
	v_pk_mul_f32 v[118:119], v[10:11], v[34:35]
	v_pk_fma_f32 v[34:35], v[18:19], v[34:35], v[98:99]
	v_pk_fma_f32 v[116:117], v[12:13], v[32:33], v[116:117]
	v_pk_fma_f32 v[32:33], v[20:21], v[32:33], v[100:101]
	v_pk_fma_f32 v[118:119], v[14:15], v[30:31], v[118:119]
	v_pk_fma_f32 v[30:31], v[22:23], v[30:31], v[102:103]
	ds_read_b128 v[8:11], v120 offset:384
	ds_read_b128 v[12:15], v120 offset:400
	ds_read_b128 v[16:19], v120 offset:8704
	ds_read_b128 v[20:23], v120 offset:8720
	v_pk_add_f32 v[116:117], v[116:117], v[118:119]
	v_pk_mul_f32 v[104:105], v[114:115], v[88:89] op_sel_hi:[0,1]
	v_pk_mul_f32 v[106:107], v[114:115], v[90:91] op_sel_hi:[0,1]
	v_add_f32_e32 v116, v116, v117
	v_pk_mul_f32 v[108:109], v[114:115], v[92:93] op_sel_hi:[0,1]
	v_pk_mul_f32 v[110:111], v[114:115], v[94:95] op_sel_hi:[0,1]
	v_add_f32_dpp v116, v116, v116 quad_perm:[1,0,3,2] row_mask:0xf bank_mask:0xf bound_ctrl:1
	ds_read_b128 v[88:91], v120 offset:4736
	ds_read_b128 v[92:95], v120 offset:4752
	ds_read_b32 v114, v121 offset:13568
	v_add_f32_dpp v116, v116, v116 quad_perm:[2,3,0,1] row_mask:0xf bank_mask:0xf bound_ctrl:1
	s_mov_b64 exec, s[38:39]
	s_waitcnt lgkmcnt(11)
	ds_write_b32 v121, v116 offset:20736
	s_mov_b64 exec, s[0:1]
	s_waitcnt lgkmcnt(9)
	v_pk_mul_f32 v[116:117], v[0:1], v[36:37]
	v_pk_fma_f32 v[36:37], v[72:73], v[36:37], v[104:105]
	v_pk_mul_f32 v[118:119], v[2:3], v[34:35]
	v_pk_fma_f32 v[34:35], v[74:75], v[34:35], v[106:107]
	v_pk_fma_f32 v[116:117], v[4:5], v[32:33], v[116:117]
	v_pk_fma_f32 v[32:33], v[76:77], v[32:33], v[108:109]
	v_pk_fma_f32 v[118:119], v[6:7], v[30:31], v[118:119]
	v_pk_fma_f32 v[30:31], v[78:79], v[30:31], v[110:111]
	ds_read_b128 v[0:3], v120 offset:512
	ds_read_b128 v[4:7], v120 offset:528
	ds_read_b128 v[72:75], v120 offset:8832
	ds_read_b128 v[76:79], v120 offset:8848
	v_pk_add_f32 v[116:117], v[116:117], v[118:119]
	v_pk_mul_f32 v[96:97], v[112:113], v[80:81] op_sel_hi:[0,1]
	v_pk_mul_f32 v[98:99], v[112:113], v[82:83] op_sel_hi:[0,1]
	v_add_f32_e32 v116, v116, v117
	v_pk_mul_f32 v[100:101], v[112:113], v[84:85] op_sel_hi:[0,1]
	v_pk_mul_f32 v[102:103], v[112:113], v[86:87] op_sel_hi:[0,1]
	v_add_f32_dpp v116, v116, v116 quad_perm:[1,0,3,2] row_mask:0xf bank_mask:0xf bound_ctrl:1
	ds_read_b128 v[80:83], v120 offset:4864
	ds_read_b128 v[84:87], v120 offset:4880
	s_waitcnt lgkmcnt(11)
; #define LAS __attribute__((address_space(3)))
; __device__ __forceinline__ float quad_sum(float v) { v += dppf<0xB1>(v); v += dppf<0x4E>(v); return v; }
; __device__ __forceinline__ void gla_unit(const Params& P, LAS unsigned char* lds, int li, bool sample, int b, int h, const int tid) {
;     ...
;             for (int tok = 0; tok < ntok; ++tok) {
;                 const int tn = min(tok + 1, ntok - 1);
;                 f32x4 kn[2], qn[2], gn[2];
; #pragma unroll
;                 for (int i = 0; i < 2; ++i) { kn[i] = *(const LAS f32x4*)(ks + tn * 32 + 8 * dq + 4 * i); qn[i] = *(const LAS f32x4*)(qs + tn * 32 + 8 * dq + 4 * i); gn[i] = *(const LAS f32x4*)(gs + tn * 32 + 8 * dq + 4 * i); }
;                 const float vn = vs[tn * 64 + e];
;                 const f32x2 v2 = (f32x2){ve, ve};
;                 f32x2 oa[2];
; #pragma unroll
;                 for (int i = 0; i < 2; ++i) {
;                     S[2 * i] = S[2 * i] * (f32x2){gg[i][0], gg[i][1]} + (f32x2){kk[i][0], kk[i][1]} * v2; S[2 * i + 1] = S[2 * i + 1] * (f32x2){gg[i][2], gg[i][3]} + (f32x2){kk[i][2], kk[i][3]} * v2;
;                     oa[i] = (f32x2){qq[i][0], qq[i][1]} * S[2 * i] + (f32x2){qq[i][2], qq[i][3]} * S[2 * i + 1];
;                 }
;                 const f32x2 os2 = oa[0] + oa[1];
;                 const float o = quad_sum(os2[0] + os2[1]);
;                 if (dq == 0) os[tok * 64 + e] = o;
; #pragma unroll
;                 for (int i = 0; i < 2; ++i) { kk[i] = kn[i]; qq[i] = qn[i]; gg[i] = gn[i]; }
;                 ve = vn;
	ds_read_b32 v112, v121 offset:13824
	v_add_f32_dpp v116, v116, v116 quad_perm:[2,3,0,1] row_mask:0xf bank_mask:0xf bound_ctrl:1
	s_mov_b64 exec, s[38:39]
	ds_write_b32 v121, v116 offset:20992
	s_mov_b64 exec, s[0:1]
	s_waitcnt lgkmcnt(9)
	v_pk_mul_f32 v[116:117], v[8:9], v[36:37]
	v_pk_fma_f32 v[36:37], v[16:17], v[36:37], v[96:97]
	v_pk_mul_f32 v[118:119], v[10:11], v[34:35]
	v_pk_fma_f32 v[34:35], v[18:19], v[34:35], v[98:99]
	v_pk_fma_f32 v[116:117], v[12:13], v[32:33], v[116:117]
	v_pk_fma_f32 v[32:33], v[20:21], v[32:33], v[100:101]
	v_pk_fma_f32 v[118:119], v[14:15], v[30:31], v[118:119]
	v_pk_fma_f32 v[30:31], v[22:23], v[30:31], v[102:103]
	ds_read_b128 v[8:11], v120 offset:640
	ds_read_b128 v[12:15], v120 offset:656
	ds_read_b128 v[16:19], v120 offset:8960
	ds_read_b128 v[20:23], v120 offset:8976
	v_pk_add_f32 v[116:117], v[116:117], v[118:119]
	v_pk_mul_f32 v[104:105], v[114:115], v[88:89] op_sel_hi:[0,1]
	v_pk_mul_f32 v[106:107], v[114:115], v[90:91] op_sel_hi:[0,1]
	v_add_f32_e32 v116, v116, v117
	v_pk_mul_f32 v[108:109], v[114:115], v[92:93] op_sel_hi:[0,1]
	v_pk_mul_f32 v[110:111], v[114:115], v[94:95] op_sel_hi:[0,1]
	v_add_f32_dpp v116, v116, v116 quad_perm:[1,0,3,2] row_mask:0xf bank_mask:0xf bound_ctrl:1
	ds_read_b128 v[88:91], v120 offset:4992
	ds_read_b128 v[92:95], v120 offset:5008
	s_waitcnt lgkmcnt(11)
	ds_read_b32 v114, v121 offset:14080
	v_add_f32_dpp v116, v116, v116 quad_perm:[2,3,0,1] row_mask:0xf bank_mask:0xf bound_ctrl:1
	s_mov_b64 exec, s[38:39]
	ds_write_b32 v121, v116 offset:21248
	s_mov_b64 exec, s[0:1]
	s_waitcnt lgkmcnt(9)
	v_pk_mul_f32 v[116:117], v[0:1], v[36:37]
	v_pk_fma_f32 v[36:37], v[72:73], v[36:37], v[104:105]
	v_pk_mul_f32 v[118:119], v[2:3], v[34:35]
	v_pk_fma_f32 v[34:35], v[74:75], v[34:35], v[106:107]
	v_pk_fma_f32 v[116:117], v[4:5], v[32:33], v[116:117]
	v_pk_fma_f32 v[32:33], v[76:77], v[32:33], v[108:109]
	v_pk_fma_f32 v[118:119], v[6:7], v[30:31], v[118:119]
	v_pk_fma_f32 v[30:31], v[78:79], v[30:31], v[110:111]
	ds_read_b128 v[0:3], v120 offset:768
	ds_read_b128 v[4:7], v120 offset:784
	ds_read_b128 v[72:75], v120 offset:9088
	ds_read_b128 v[76:79], v120 offset:9104
	v_pk_add_f32 v[116:117], v[116:117], v[118:119]
	v_pk_mul_f32 v[96:97], v[112:113], v[80:81] op_sel_hi:[0,1]
	v_pk_mul_f32 v[98:99], v[112:113], v[82:83] op_sel_hi:[0,1]
	v_add_f32_e32 v116, v116, v117
	v_pk_mul_f32 v[100:101], v[112:113], v[84:85] op_sel_hi:[0,1]
	v_pk_mul_f32 v[102:103], v[112:113], v[86:87] op_sel_hi:[0,1]
	v_add_f32_dpp v116, v116, v116 quad_perm:[1,0,3,2] row_mask:0xf bank_mask:0xf bound_ctrl:1
	ds_read_b128 v[80:83], v120 offset:5120
	ds_read_b128 v[84:87], v120 offset:5136
	s_waitcnt lgkmcnt(11)
	ds_read_b32 v112, v121 offset:14336
	v_add_f32_dpp v116, v116, v116 quad_perm:[2,3,0,1] row_mask:0xf bank_mask:0xf bound_ctrl:1
	s_mov_b64 exec, s[38:39]
	ds_write_b32 v121, v116 offset:21504
	s_mov_b64 exec, s[0:1]
	s_waitcnt lgkmcnt(9)
	v_pk_mul_f32 v[116:117], v[8:9], v[36:37]
	v_pk_fma_f32 v[36:37], v[16:17], v[36:37], v[96:97]
	v_pk_mul_f32 v[118:119], v[10:11], v[34:35]
	v_pk_fma_f32 v[34:35], v[18:19], v[34:35], v[98:99]
	v_pk_fma_f32 v[116:117], v[12:13], v[32:33], v[116:117]
	v_pk_fma_f32 v[32:33], v[20:21], v[32:33], v[100:101]
	v_pk_fma_f32 v[118:119], v[14:15], v[30:31], v[118:119]
	v_pk_fma_f32 v[30:31], v[22:23], v[30:31], v[102:103]
	ds_read_b128 v[8:11], v120 offset:896
	ds_read_b128 v[12:15], v120 offset:912
	ds_read_b128 v[16:19], v120 offset:9216
	ds_read_b128 v[20:23], v120 offset:9232
	v_pk_add_f32 v[116:117], v[116:117], v[118:119]
	v_pk_mul_f32 v[104:105], v[114:115], v[88:89] op_sel_hi:[0,1]
	v_pk_mul_f32 v[106:107], v[114:115], v[90:91] op_sel_hi:[0,1]
	v_add_f32_e32 v116, v116, v117
	v_pk_mul_f32 v[108:109], v[114:115], v[92:93] op_sel_hi:[0,1]
	v_pk_mul_f32 v[110:111], v[114:115], v[94:95] op_sel_hi:[0,1]
	v_add_f32_dpp v116, v116, v116 quad_perm:[1,0,3,2] row_mask:0xf bank_mask:0xf bound_ctrl:1
	ds_read_b128 v[88:91], v120 offset:5248
	ds_read_b128 v[92:95], v120 offset:5264
	s_waitcnt lgkmcnt(11)
	ds_read_b32 v114, v121 offset:14592
	v_add_f32_dpp v116, v116, v116 quad_perm:[2,3,0,1] row_mask:0xf bank_mask:0xf bound_ctrl:1
	s_mov_b64 exec, s[38:39]
	ds_write_b32 v121, v116 offset:21760
	s_mov_b64 exec, s[0:1]
	s_waitcnt lgkmcnt(9)
	v_pk_mul_f32 v[116:117], v[0:1], v[36:37]
	v_pk_fma_f32 v[36:37], v[72:73], v[36:37], v[104:105]
	v_pk_mul_f32 v[118:119], v[2:3], v[34:35]
	v_pk_fma_f32 v[34:35], v[74:75], v[34:35], v[106:107]
	v_pk_fma_f32 v[116:117], v[4:5], v[32:33], v[116:117]
	v_pk_fma_f32 v[32:33], v[76:77], v[32:33], v[108:109]
	v_pk_fma_f32 v[118:119], v[6:7], v[30:31], v[118:119]
	v_pk_fma_f32 v[30:31], v[78:79], v[30:31], v[110:111]
	ds_read_b128 v[0:3], v120 offset:1024
	ds_read_b128 v[4:7], v120 offset:1040
	ds_read_b128 v[72:75], v120 offset:9344
	ds_read_b128 v[76:79], v120 offset:9360
	v_pk_add_f32 v[116:117], v[116:117], v[118:119]
	v_pk_mul_f32 v[96:97], v[112:113], v[80:81] op_sel_hi:[0,1]
	v_pk_mul_f32 v[98:99], v[112:113], v[82:83] op_sel_hi:[0,1]
	v_add_f32_e32 v116, v116, v117
	v_pk_mul_f32 v[100:101], v[112:113], v[84:85] op_sel_hi:[0,1]
	v_pk_mul_f32 v[102:103], v[112:113], v[86:87] op_sel_hi:[0,1]
	v_add_f32_dpp v116, v116, v116 quad_perm:[1,0,3,2] row_mask:0xf bank_mask:0xf bound_ctrl:1
	ds_read_b128 v[80:83], v120 offset:5376
	ds_read_b128 v[84:87], v120 offset:5392
	s_waitcnt lgkmcnt(11)
	ds_read_b32 v112, v121 offset:14848
	v_add_f32_dpp v116, v116, v116 quad_perm:[2,3,0,1] row_mask:0xf bank_mask:0xf bound_ctrl:1
	s_mov_b64 exec, s[38:39]
	ds_write_b32 v121, v116 offset:22016
	s_mov_b64 exec, s[0:1]
	s_waitcnt lgkmcnt(9)
; #define LAS __attribute__((address_space(3)))
; __device__ __forceinline__ float quad_sum(float v) { v += dppf<0xB1>(v); v += dppf<0x4E>(v); return v; }
; __device__ __forceinline__ void gla_unit(const Params& P, LAS unsigned char* lds, int li, bool sample, int b, int h, const int tid) {
;     ...
;             for (int tok = 0; tok < ntok; ++tok) {
;                 const int tn = min(tok + 1, ntok - 1);
;                 f32x4 kn[2], qn[2], gn[2];
; #pragma unroll
;                 for (int i = 0; i < 2; ++i) { kn[i] = *(const LAS f32x4*)(ks + tn * 32 + 8 * dq + 4 * i); qn[i] = *(const LAS f32x4*)(qs + tn * 32 + 8 * dq + 4 * i); gn[i] = *(const LAS f32x4*)(gs + tn * 32 + 8 * dq + 4 * i); }
;                 const float vn = vs[tn * 64 + e];
;                 const f32x2 v2 = (f32x2){ve, ve};
;                 f32x2 oa[2];
; #pragma unroll
;                 for (int i = 0; i < 2; ++i) {
;                     S[2 * i] = S[2 * i] * (f32x2){gg[i][0], gg[i][1]} + (f32x2){kk[i][0], kk[i][1]} * v2; S[2 * i + 1] = S[2 * i + 1] * (f32x2){gg[i][2], gg[i][3]} + (f32x2){kk[i][2], kk[i][3]} * v2;
;                     oa[i] = (f32x2){qq[i][0], qq[i][1]} * S[2 * i] + (f32x2){qq[i][2], qq[i][3]} * S[2 * i + 1];
;                 }
;                 const f32x2 os2 = oa[0] + oa[1];
;                 const float o = quad_sum(os2[0] + os2[1]);
;                 if (dq == 0) os[tok * 64 + e] = o;
; #pragma unroll
;                 for (int i = 0; i < 2; ++i) { kk[i] = kn[i]; qq[i] = qn[i]; gg[i] = gn[i]; }
;                 ve = vn;
	v_pk_mul_f32 v[116:117], v[8:9], v[36:37]
	v_pk_fma_f32 v[36:37], v[16:17], v[36:37], v[96:97]
	v_pk_mul_f32 v[118:119], v[10:11], v[34:35]
	v_pk_fma_f32 v[34:35], v[18:19], v[34:35], v[98:99]
	v_pk_fma_f32 v[116:117], v[12:13], v[32:33], v[116:117]
	v_pk_fma_f32 v[32:33], v[20:21], v[32:33], v[100:101]
	v_pk_fma_f32 v[118:119], v[14:15], v[30:31], v[118:119]
	v_pk_fma_f32 v[30:31], v[22:23], v[30:31], v[102:103]
	ds_read_b128 v[8:11], v120 offset:1152
	ds_read_b128 v[12:15], v120 offset:1168
	ds_read_b128 v[16:19], v120 offset:9472
	ds_read_b128 v[20:23], v120 offset:9488
	v_pk_add_f32 v[116:117], v[116:117], v[118:119]
	v_pk_mul_f32 v[104:105], v[114:115], v[88:89] op_sel_hi:[0,1]
	v_pk_mul_f32 v[106:107], v[114:115], v[90:91] op_sel_hi:[0,1]
	v_add_f32_e32 v116, v116, v117
	v_pk_mul_f32 v[108:109], v[114:115], v[92:93] op_sel_hi:[0,1]
	v_pk_mul_f32 v[110:111], v[114:115], v[94:95] op_sel_hi:[0,1]
	v_add_f32_dpp v116, v116, v116 quad_perm:[1,0,3,2] row_mask:0xf bank_mask:0xf bound_ctrl:1
	ds_read_b128 v[88:91], v120 offset:5504
	ds_read_b128 v[92:95], v120 offset:5520
	s_waitcnt lgkmcnt(11)
	ds_read_b32 v114, v121 offset:15104
	v_add_f32_dpp v116, v116, v116 quad_perm:[2,3,0,1] row_mask:0xf bank_mask:0xf bound_ctrl:1
	s_mov_b64 exec, s[38:39]
	ds_write_b32 v121, v116 offset:22272
	s_mov_b64 exec, s[0:1]
	s_waitcnt lgkmcnt(9)
	v_pk_mul_f32 v[116:117], v[0:1], v[36:37]
	v_pk_fma_f32 v[36:37], v[72:73], v[36:37], v[104:105]
	v_pk_mul_f32 v[118:119], v[2:3], v[34:35]
	v_pk_fma_f32 v[34:35], v[74:75], v[34:35], v[106:107]
	v_pk_fma_f32 v[116:117], v[4:5], v[32:33], v[116:117]
	v_pk_fma_f32 v[32:33], v[76:77], v[32:33], v[108:109]
	v_pk_fma_f32 v[118:119], v[6:7], v[30:31], v[118:119]
	v_pk_fma_f32 v[30:31], v[78:79], v[30:31], v[110:111]
	ds_read_b128 v[0:3], v120 offset:1280
	ds_read_b128 v[4:7], v120 offset:1296
	ds_read_b128 v[72:75], v120 offset:9600
	ds_read_b128 v[76:79], v120 offset:9616
	v_pk_add_f32 v[116:117], v[116:117], v[118:119]
	v_pk_mul_f32 v[96:97], v[112:113], v[80:81] op_sel_hi:[0,1]
	v_pk_mul_f32 v[98:99], v[112:113], v[82:83] op_sel_hi:[0,1]
	v_add_f32_e32 v116, v116, v117
	v_pk_mul_f32 v[100:101], v[112:113], v[84:85] op_sel_hi:[0,1]
	v_pk_mul_f32 v[102:103], v[112:113], v[86:87] op_sel_hi:[0,1]
	v_add_f32_dpp v116, v116, v116 quad_perm:[1,0,3,2] row_mask:0xf bank_mask:0xf bound_ctrl:1
	ds_read_b128 v[80:83], v120 offset:5632
	ds_read_b128 v[84:87], v120 offset:5648
	s_waitcnt lgkmcnt(11)
	ds_read_b32 v112, v121 offset:15360
	v_add_f32_dpp v116, v116, v116 quad_perm:[2,3,0,1] row_mask:0xf bank_mask:0xf bound_ctrl:1
	s_mov_b64 exec, s[38:39]
	ds_write_b32 v121, v116 offset:22528
	s_mov_b64 exec, s[0:1]
	s_waitcnt lgkmcnt(9)
	v_pk_mul_f32 v[116:117], v[8:9], v[36:37]
	v_pk_fma_f32 v[36:37], v[16:17], v[36:37], v[96:97]
	v_pk_mul_f32 v[118:119], v[10:11], v[34:35]
	v_pk_fma_f32 v[34:35], v[18:19], v[34:35], v[98:99]
	v_pk_fma_f32 v[116:117], v[12:13], v[32:33], v[116:117]
	v_pk_fma_f32 v[32:33], v[20:21], v[32:33], v[100:101]
	v_pk_fma_f32 v[118:119], v[14:15], v[30:31], v[118:119]
	v_pk_fma_f32 v[30:31], v[22:23], v[30:31], v[102:103]
	ds_read_b128 v[8:11], v120 offset:1408
	ds_read_b128 v[12:15], v120 offset:1424
	ds_read_b128 v[16:19], v120 offset:9728
	ds_read_b128 v[20:23], v120 offset:9744
	v_pk_add_f32 v[116:117], v[116:117], v[118:119]
	v_pk_mul_f32 v[104:105], v[114:115], v[88:89] op_sel_hi:[0,1]
	v_pk_mul_f32 v[106:107], v[114:115], v[90:91] op_sel_hi:[0,1]
	v_add_f32_e32 v116, v116, v117
	v_pk_mul_f32 v[108:109], v[114:115], v[92:93] op_sel_hi:[0,1]
	v_pk_mul_f32 v[110:111], v[114:115], v[94:95] op_sel_hi:[0,1]
	v_add_f32_dpp v116, v116, v116 quad_perm:[1,0,3,2] row_mask:0xf bank_mask:0xf bound_ctrl:1
	ds_read_b128 v[88:91], v120 offset:5760
	ds_read_b128 v[92:95], v120 offset:5776
	s_waitcnt lgkmcnt(11)
	ds_read_b32 v114, v121 offset:15616
	v_add_f32_dpp v116, v116, v116 quad_perm:[2,3,0,1] row_mask:0xf bank_mask:0xf bound_ctrl:1
	s_mov_b64 exec, s[38:39]
	ds_write_b32 v121, v116 offset:22784
	s_mov_b64 exec, s[0:1]
	s_waitcnt lgkmcnt(9)
	v_pk_mul_f32 v[116:117], v[0:1], v[36:37]
	v_pk_fma_f32 v[36:37], v[72:73], v[36:37], v[104:105]
	v_pk_mul_f32 v[118:119], v[2:3], v[34:35]
	v_pk_fma_f32 v[34:35], v[74:75], v[34:35], v[106:107]
	v_pk_fma_f32 v[116:117], v[4:5], v[32:33], v[116:117]
	v_pk_fma_f32 v[32:33], v[76:77], v[32:33], v[108:109]
	v_pk_fma_f32 v[118:119], v[6:7], v[30:31], v[118:119]
	v_pk_fma_f32 v[30:31], v[78:79], v[30:31], v[110:111]
	ds_read_b128 v[0:3], v120 offset:1536
	ds_read_b128 v[4:7], v120 offset:1552
	ds_read_b128 v[72:75], v120 offset:9856
	ds_read_b128 v[76:79], v120 offset:9872
	v_pk_add_f32 v[116:117], v[116:117], v[118:119]
	v_pk_mul_f32 v[96:97], v[112:113], v[80:81] op_sel_hi:[0,1]
	v_pk_mul_f32 v[98:99], v[112:113], v[82:83] op_sel_hi:[0,1]
	v_add_f32_e32 v116, v116, v117
	v_pk_mul_f32 v[100:101], v[112:113], v[84:85] op_sel_hi:[0,1]
	v_pk_mul_f32 v[102:103], v[112:113], v[86:87] op_sel_hi:[0,1]
	v_add_f32_dpp v116, v116, v116 quad_perm:[1,0,3,2] row_mask:0xf bank_mask:0xf bound_ctrl:1
	ds_read_b128 v[80:83], v120 offset:5888
	ds_read_b128 v[84:87], v120 offset:5904
	s_waitcnt lgkmcnt(11)
	ds_read_b32 v112, v121 offset:15872
	v_add_f32_dpp v116, v116, v116 quad_perm:[2,3,0,1] row_mask:0xf bank_mask:0xf bound_ctrl:1
	s_mov_b64 exec, s[38:39]
	ds_write_b32 v121, v116 offset:23040
	s_mov_b64 exec, s[0:1]
	s_waitcnt lgkmcnt(9)
; #define LAS __attribute__((address_space(3)))
; __device__ __forceinline__ float quad_sum(float v) { v += dppf<0xB1>(v); v += dppf<0x4E>(v); return v; }
; __device__ __forceinline__ void gla_unit(const Params& P, LAS unsigned char* lds, int li, bool sample, int b, int h, const int tid) {
;     ...
;             for (int tok = 0; tok < ntok; ++tok) {
;                 const int tn = min(tok + 1, ntok - 1);
;                 f32x4 kn[2], qn[2], gn[2];
; #pragma unroll
;                 for (int i = 0; i < 2; ++i) { kn[i] = *(const LAS f32x4*)(ks + tn * 32 + 8 * dq + 4 * i); qn[i] = *(const LAS f32x4*)(qs + tn * 32 + 8 * dq + 4 * i); gn[i] = *(const LAS f32x4*)(gs + tn * 32 + 8 * dq + 4 * i); }
;                 const float vn = vs[tn * 64 + e];
;                 const f32x2 v2 = (f32x2){ve, ve};
;                 f32x2 oa[2];
; #pragma unroll
;                 for (int i = 0; i < 2; ++i) {
;                     S[2 * i] = S[2 * i] * (f32x2){gg[i][0], gg[i][1]} + (f32x2){kk[i][0], kk[i][1]} * v2; S[2 * i + 1] = S[2 * i + 1] * (f32x2){gg[i][2], gg[i][3]} + (f32x2){kk[i][2], kk[i][3]} * v2;
;                     oa[i] = (f32x2){qq[i][0], qq[i][1]} * S[2 * i] + (f32x2){qq[i][2], qq[i][3]} * S[2 * i + 1];
;                 }
;                 const f32x2 os2 = oa[0] + oa[1];
;                 const float o = quad_sum(os2[0] + os2[1]);
;                 if (dq == 0) os[tok * 64 + e] = o;
; #pragma unroll
;                 for (int i = 0; i < 2; ++i) { kk[i] = kn[i]; qq[i] = qn[i]; gg[i] = gn[i]; }
;                 ve = vn;
	v_pk_mul_f32 v[116:117], v[8:9], v[36:37]
	v_pk_fma_f32 v[36:37], v[16:17], v[36:37], v[96:97]
	v_pk_mul_f32 v[118:119], v[10:11], v[34:35]
	v_pk_fma_f32 v[34:35], v[18:19], v[34:35], v[98:99]
	v_pk_fma_f32 v[116:117], v[12:13], v[32:33], v[116:117]
	v_pk_fma_f32 v[32:33], v[20:21], v[32:33], v[100:101]
	v_pk_fma_f32 v[118:119], v[14:15], v[30:31], v[118:119]
	v_pk_fma_f32 v[30:31], v[22:23], v[30:31], v[102:103]
	ds_read_b128 v[8:11], v120 offset:1664
	ds_read_b128 v[12:15], v120 offset:1680
	ds_read_b128 v[16:19], v120 offset:9984
	ds_read_b128 v[20:23], v120 offset:10000
	v_pk_add_f32 v[116:117], v[116:117], v[118:119]
	v_pk_mul_f32 v[104:105], v[114:115], v[88:89] op_sel_hi:[0,1]
	v_pk_mul_f32 v[106:107], v[114:115], v[90:91] op_sel_hi:[0,1]
	v_add_f32_e32 v116, v116, v117
	v_pk_mul_f32 v[108:109], v[114:115], v[92:93] op_sel_hi:[0,1]
	v_pk_mul_f32 v[110:111], v[114:115], v[94:95] op_sel_hi:[0,1]
	v_add_f32_dpp v116, v116, v116 quad_perm:[1,0,3,2] row_mask:0xf bank_mask:0xf bound_ctrl:1
	ds_read_b128 v[88:91], v120 offset:6016
	ds_read_b128 v[92:95], v120 offset:6032
	s_waitcnt lgkmcnt(11)
	ds_read_b32 v114, v121 offset:16128
	v_add_f32_dpp v116, v116, v116 quad_perm:[2,3,0,1] row_mask:0xf bank_mask:0xf bound_ctrl:1
	s_mov_b64 exec, s[38:39]
	ds_write_b32 v121, v116 offset:23296
	s_mov_b64 exec, s[0:1]
	s_waitcnt lgkmcnt(9)
	v_pk_mul_f32 v[116:117], v[0:1], v[36:37]
	v_pk_fma_f32 v[36:37], v[72:73], v[36:37], v[104:105]
	v_pk_mul_f32 v[118:119], v[2:3], v[34:35]
	v_pk_fma_f32 v[34:35], v[74:75], v[34:35], v[106:107]
	v_pk_fma_f32 v[116:117], v[4:5], v[32:33], v[116:117]
	v_pk_fma_f32 v[32:33], v[76:77], v[32:33], v[108:109]
	v_pk_fma_f32 v[118:119], v[6:7], v[30:31], v[118:119]
	v_pk_fma_f32 v[30:31], v[78:79], v[30:31], v[110:111]
	ds_read_b128 v[0:3], v120 offset:1792
	ds_read_b128 v[4:7], v120 offset:1808
	ds_read_b128 v[72:75], v120 offset:10112
	ds_read_b128 v[76:79], v120 offset:10128
	v_pk_add_f32 v[116:117], v[116:117], v[118:119]
	v_pk_mul_f32 v[96:97], v[112:113], v[80:81] op_sel_hi:[0,1]
	v_pk_mul_f32 v[98:99], v[112:113], v[82:83] op_sel_hi:[0,1]
	v_add_f32_e32 v116, v116, v117
	v_pk_mul_f32 v[100:101], v[112:113], v[84:85] op_sel_hi:[0,1]
	v_pk_mul_f32 v[102:103], v[112:113], v[86:87] op_sel_hi:[0,1]
	v_add_f32_dpp v116, v116, v116 quad_perm:[1,0,3,2] row_mask:0xf bank_mask:0xf bound_ctrl:1
	ds_read_b128 v[80:83], v120 offset:6144
	ds_read_b128 v[84:87], v120 offset:6160
	s_waitcnt lgkmcnt(11)
	ds_read_b32 v112, v121 offset:16384
	v_add_f32_dpp v116, v116, v116 quad_perm:[2,3,0,1] row_mask:0xf bank_mask:0xf bound_ctrl:1
	s_mov_b64 exec, s[38:39]
	ds_write_b32 v121, v116 offset:23552
	s_mov_b64 exec, s[0:1]
	s_waitcnt lgkmcnt(9)
	v_pk_mul_f32 v[116:117], v[8:9], v[36:37]
	v_pk_fma_f32 v[36:37], v[16:17], v[36:37], v[96:97]
	v_pk_mul_f32 v[118:119], v[10:11], v[34:35]
	v_pk_fma_f32 v[34:35], v[18:19], v[34:35], v[98:99]
	v_pk_fma_f32 v[116:117], v[12:13], v[32:33], v[116:117]
	v_pk_fma_f32 v[32:33], v[20:21], v[32:33], v[100:101]
	v_pk_fma_f32 v[118:119], v[14:15], v[30:31], v[118:119]
	v_pk_fma_f32 v[30:31], v[22:23], v[30:31], v[102:103]
	ds_read_b128 v[8:11], v120 offset:1920
	ds_read_b128 v[12:15], v120 offset:1936
	ds_read_b128 v[16:19], v120 offset:10240
	ds_read_b128 v[20:23], v120 offset:10256
	v_pk_add_f32 v[116:117], v[116:117], v[118:119]
	v_pk_mul_f32 v[104:105], v[114:115], v[88:89] op_sel_hi:[0,1]
	v_pk_mul_f32 v[106:107], v[114:115], v[90:91] op_sel_hi:[0,1]
	v_add_f32_e32 v116, v116, v117
	v_pk_mul_f32 v[108:109], v[114:115], v[92:93] op_sel_hi:[0,1]
	v_pk_mul_f32 v[110:111], v[114:115], v[94:95] op_sel_hi:[0,1]
	v_add_f32_dpp v116, v116, v116 quad_perm:[1,0,3,2] row_mask:0xf bank_mask:0xf bound_ctrl:1
	ds_read_b128 v[88:91], v120 offset:6272
	ds_read_b128 v[92:95], v120 offset:6288
	s_waitcnt lgkmcnt(11)
	ds_read_b32 v114, v121 offset:16640
	v_add_f32_dpp v116, v116, v116 quad_perm:[2,3,0,1] row_mask:0xf bank_mask:0xf bound_ctrl:1
	s_mov_b64 exec, s[38:39]
	ds_write_b32 v121, v116 offset:23808
	s_mov_b64 exec, s[0:1]
	s_waitcnt lgkmcnt(9)
	v_pk_mul_f32 v[116:117], v[0:1], v[36:37]
	v_pk_fma_f32 v[36:37], v[72:73], v[36:37], v[104:105]
	v_pk_mul_f32 v[118:119], v[2:3], v[34:35]
	v_pk_fma_f32 v[34:35], v[74:75], v[34:35], v[106:107]
	v_pk_fma_f32 v[116:117], v[4:5], v[32:33], v[116:117]
	v_pk_fma_f32 v[32:33], v[76:77], v[32:33], v[108:109]
	v_pk_fma_f32 v[118:119], v[6:7], v[30:31], v[118:119]
	v_pk_fma_f32 v[30:31], v[78:79], v[30:31], v[110:111]
	ds_read_b128 v[0:3], v120 offset:2048
	ds_read_b128 v[4:7], v120 offset:2064
	ds_read_b128 v[72:75], v120 offset:10368
	ds_read_b128 v[76:79], v120 offset:10384
	v_pk_add_f32 v[116:117], v[116:117], v[118:119]
	v_pk_mul_f32 v[96:97], v[112:113], v[80:81] op_sel_hi:[0,1]
	v_pk_mul_f32 v[98:99], v[112:113], v[82:83] op_sel_hi:[0,1]
	v_add_f32_e32 v116, v116, v117
	v_pk_mul_f32 v[100:101], v[112:113], v[84:85] op_sel_hi:[0,1]
	v_pk_mul_f32 v[102:103], v[112:113], v[86:87] op_sel_hi:[0,1]
	v_add_f32_dpp v116, v116, v116 quad_perm:[1,0,3,2] row_mask:0xf bank_mask:0xf bound_ctrl:1
	ds_read_b128 v[80:83], v120 offset:6400
	ds_read_b128 v[84:87], v120 offset:6416
	s_waitcnt lgkmcnt(11)
	ds_read_b32 v112, v121 offset:16896
	v_add_f32_dpp v116, v116, v116 quad_perm:[2,3,0,1] row_mask:0xf bank_mask:0xf bound_ctrl:1
	s_mov_b64 exec, s[38:39]
	ds_write_b32 v121, v116 offset:24064
	s_mov_b64 exec, s[0:1]
	s_waitcnt lgkmcnt(9)
; #define LAS __attribute__((address_space(3)))
; __device__ __forceinline__ float quad_sum(float v) { v += dppf<0xB1>(v); v += dppf<0x4E>(v); return v; }
; __device__ __forceinline__ void gla_unit(const Params& P, LAS unsigned char* lds, int li, bool sample, int b, int h, const int tid) {
;     ...
;             for (int tok = 0; tok < ntok; ++tok) {
;                 const int tn = min(tok + 1, ntok - 1);
;                 f32x4 kn[2], qn[2], gn[2];
; #pragma unroll
;                 for (int i = 0; i < 2; ++i) { kn[i] = *(const LAS f32x4*)(ks + tn * 32 + 8 * dq + 4 * i); qn[i] = *(const LAS f32x4*)(qs + tn * 32 + 8 * dq + 4 * i); gn[i] = *(const LAS f32x4*)(gs + tn * 32 + 8 * dq + 4 * i); }
;                 const float vn = vs[tn * 64 + e];
;                 const f32x2 v2 = (f32x2){ve, ve};
;                 f32x2 oa[2];
; #pragma unroll
;                 for (int i = 0; i < 2; ++i) {
;                     S[2 * i] = S[2 * i] * (f32x2){gg[i][0], gg[i][1]} + (f32x2){kk[i][0], kk[i][1]} * v2; S[2 * i + 1] = S[2 * i + 1] * (f32x2){gg[i][2], gg[i][3]} + (f32x2){kk[i][2], kk[i][3]} * v2;
;                     oa[i] = (f32x2){qq[i][0], qq[i][1]} * S[2 * i] + (f32x2){qq[i][2], qq[i][3]} * S[2 * i + 1];
;                 }
;                 const f32x2 os2 = oa[0] + oa[1];
;                 const float o = quad_sum(os2[0] + os2[1]);
;                 if (dq == 0) os[tok * 64 + e] = o;
; #pragma unroll
;                 for (int i = 0; i < 2; ++i) { kk[i] = kn[i]; qq[i] = qn[i]; gg[i] = gn[i]; }
;                 ve = vn;
	v_pk_mul_f32 v[116:117], v[8:9], v[36:37]
	v_pk_fma_f32 v[36:37], v[16:17], v[36:37], v[96:97]
	v_pk_mul_f32 v[118:119], v[10:11], v[34:35]
	v_pk_fma_f32 v[34:35], v[18:19], v[34:35], v[98:99]
	v_pk_fma_f32 v[116:117], v[12:13], v[32:33], v[116:117]
	v_pk_fma_f32 v[32:33], v[20:21], v[32:33], v[100:101]
	v_pk_fma_f32 v[118:119], v[14:15], v[30:31], v[118:119]
	v_pk_fma_f32 v[30:31], v[22:23], v[30:31], v[102:103]
	ds_read_b128 v[8:11], v120 offset:2176
	ds_read_b128 v[12:15], v120 offset:2192
	ds_read_b128 v[16:19], v120 offset:10496
	ds_read_b128 v[20:23], v120 offset:10512
	v_pk_add_f32 v[116:117], v[116:117], v[118:119]
	v_pk_mul_f32 v[104:105], v[114:115], v[88:89] op_sel_hi:[0,1]
	v_pk_mul_f32 v[106:107], v[114:115], v[90:91] op_sel_hi:[0,1]
	v_add_f32_e32 v116, v116, v117
	v_pk_mul_f32 v[108:109], v[114:115], v[92:93] op_sel_hi:[0,1]
	v_pk_mul_f32 v[110:111], v[114:115], v[94:95] op_sel_hi:[0,1]
	v_add_f32_dpp v116, v116, v116 quad_perm:[1,0,3,2] row_mask:0xf bank_mask:0xf bound_ctrl:1
	ds_read_b128 v[88:91], v120 offset:6528
	ds_read_b128 v[92:95], v120 offset:6544
	s_waitcnt lgkmcnt(11)
	ds_read_b32 v114, v121 offset:17152
	v_add_f32_dpp v116, v116, v116 quad_perm:[2,3,0,1] row_mask:0xf bank_mask:0xf bound_ctrl:1
	s_mov_b64 exec, s[38:39]
	ds_write_b32 v121, v116 offset:24320
	s_mov_b64 exec, s[0:1]
	s_waitcnt lgkmcnt(9)
	v_pk_mul_f32 v[116:117], v[0:1], v[36:37]
	v_pk_fma_f32 v[36:37], v[72:73], v[36:37], v[104:105]
	v_pk_mul_f32 v[118:119], v[2:3], v[34:35]
	v_pk_fma_f32 v[34:35], v[74:75], v[34:35], v[106:107]
	v_pk_fma_f32 v[116:117], v[4:5], v[32:33], v[116:117]
	v_pk_fma_f32 v[32:33], v[76:77], v[32:33], v[108:109]
	v_pk_fma_f32 v[118:119], v[6:7], v[30:31], v[118:119]
	v_pk_fma_f32 v[30:31], v[78:79], v[30:31], v[110:111]
	ds_read_b128 v[0:3], v120 offset:2304
	ds_read_b128 v[4:7], v120 offset:2320
	ds_read_b128 v[72:75], v120 offset:10624
	ds_read_b128 v[76:79], v120 offset:10640
	v_pk_add_f32 v[116:117], v[116:117], v[118:119]
	v_pk_mul_f32 v[96:97], v[112:113], v[80:81] op_sel_hi:[0,1]
	v_pk_mul_f32 v[98:99], v[112:113], v[82:83] op_sel_hi:[0,1]
	v_add_f32_e32 v116, v116, v117
	v_pk_mul_f32 v[100:101], v[112:113], v[84:85] op_sel_hi:[0,1]
	v_pk_mul_f32 v[102:103], v[112:113], v[86:87] op_sel_hi:[0,1]
	v_add_f32_dpp v116, v116, v116 quad_perm:[1,0,3,2] row_mask:0xf bank_mask:0xf bound_ctrl:1
	ds_read_b128 v[80:83], v120 offset:6656
	ds_read_b128 v[84:87], v120 offset:6672
	s_waitcnt lgkmcnt(11)
	ds_read_b32 v112, v121 offset:17408
	v_add_f32_dpp v116, v116, v116 quad_perm:[2,3,0,1] row_mask:0xf bank_mask:0xf bound_ctrl:1
	s_mov_b64 exec, s[38:39]
	ds_write_b32 v121, v116 offset:24576
	s_mov_b64 exec, s[0:1]
	s_waitcnt lgkmcnt(9)
	v_pk_mul_f32 v[116:117], v[8:9], v[36:37]
	v_pk_fma_f32 v[36:37], v[16:17], v[36:37], v[96:97]
	v_pk_mul_f32 v[118:119], v[10:11], v[34:35]
	v_pk_fma_f32 v[34:35], v[18:19], v[34:35], v[98:99]
	v_pk_fma_f32 v[116:117], v[12:13], v[32:33], v[116:117]
	v_pk_fma_f32 v[32:33], v[20:21], v[32:33], v[100:101]
	v_pk_fma_f32 v[118:119], v[14:15], v[30:31], v[118:119]
	v_pk_fma_f32 v[30:31], v[22:23], v[30:31], v[102:103]
	ds_read_b128 v[8:11], v120 offset:2432
	ds_read_b128 v[12:15], v120 offset:2448
	ds_read_b128 v[16:19], v120 offset:10752
	ds_read_b128 v[20:23], v120 offset:10768
	v_pk_add_f32 v[116:117], v[116:117], v[118:119]
	v_pk_mul_f32 v[104:105], v[114:115], v[88:89] op_sel_hi:[0,1]
	v_pk_mul_f32 v[106:107], v[114:115], v[90:91] op_sel_hi:[0,1]
	v_add_f32_e32 v116, v116, v117
	v_pk_mul_f32 v[108:109], v[114:115], v[92:93] op_sel_hi:[0,1]
	v_pk_mul_f32 v[110:111], v[114:115], v[94:95] op_sel_hi:[0,1]
	v_add_f32_dpp v116, v116, v116 quad_perm:[1,0,3,2] row_mask:0xf bank_mask:0xf bound_ctrl:1
	ds_read_b128 v[88:91], v120 offset:6784
	ds_read_b128 v[92:95], v120 offset:6800
	s_waitcnt lgkmcnt(11)
	ds_read_b32 v114, v121 offset:17664
	v_add_f32_dpp v116, v116, v116 quad_perm:[2,3,0,1] row_mask:0xf bank_mask:0xf bound_ctrl:1
	s_mov_b64 exec, s[38:39]
	ds_write_b32 v121, v116 offset:24832
	s_mov_b64 exec, s[0:1]
	s_waitcnt lgkmcnt(9)
	v_pk_mul_f32 v[116:117], v[0:1], v[36:37]
	v_pk_fma_f32 v[36:37], v[72:73], v[36:37], v[104:105]
	v_pk_mul_f32 v[118:119], v[2:3], v[34:35]
	v_pk_fma_f32 v[34:35], v[74:75], v[34:35], v[106:107]
	v_pk_fma_f32 v[116:117], v[4:5], v[32:33], v[116:117]
	v_pk_fma_f32 v[32:33], v[76:77], v[32:33], v[108:109]
	v_pk_fma_f32 v[118:119], v[6:7], v[30:31], v[118:119]
	v_pk_fma_f32 v[30:31], v[78:79], v[30:31], v[110:111]
	ds_read_b128 v[0:3], v120 offset:2560
	ds_read_b128 v[4:7], v120 offset:2576
	ds_read_b128 v[72:75], v120 offset:10880
	ds_read_b128 v[76:79], v120 offset:10896
	v_pk_add_f32 v[116:117], v[116:117], v[118:119]
	v_pk_mul_f32 v[96:97], v[112:113], v[80:81] op_sel_hi:[0,1]
	v_pk_mul_f32 v[98:99], v[112:113], v[82:83] op_sel_hi:[0,1]
	v_add_f32_e32 v116, v116, v117
	v_pk_mul_f32 v[100:101], v[112:113], v[84:85] op_sel_hi:[0,1]
	v_pk_mul_f32 v[102:103], v[112:113], v[86:87] op_sel_hi:[0,1]
	v_add_f32_dpp v116, v116, v116 quad_perm:[1,0,3,2] row_mask:0xf bank_mask:0xf bound_ctrl:1
	ds_read_b128 v[80:83], v120 offset:6912
	ds_read_b128 v[84:87], v120 offset:6928
	s_waitcnt lgkmcnt(11)
	ds_read_b32 v112, v121 offset:17920
	v_add_f32_dpp v116, v116, v116 quad_perm:[2,3,0,1] row_mask:0xf bank_mask:0xf bound_ctrl:1
	s_mov_b64 exec, s[38:39]
	ds_write_b32 v121, v116 offset:25088
	s_mov_b64 exec, s[0:1]
	s_waitcnt lgkmcnt(9)
; #define LAS __attribute__((address_space(3)))
; __device__ __forceinline__ float quad_sum(float v) { v += dppf<0xB1>(v); v += dppf<0x4E>(v); return v; }
; __device__ __forceinline__ void gla_unit(const Params& P, LAS unsigned char* lds, int li, bool sample, int b, int h, const int tid) {
;     ...
;             for (int tok = 0; tok < ntok; ++tok) {
;                 const int tn = min(tok + 1, ntok - 1);
;                 f32x4 kn[2], qn[2], gn[2];
; #pragma unroll
;                 for (int i = 0; i < 2; ++i) { kn[i] = *(const LAS f32x4*)(ks + tn * 32 + 8 * dq + 4 * i); qn[i] = *(const LAS f32x4*)(qs + tn * 32 + 8 * dq + 4 * i); gn[i] = *(const LAS f32x4*)(gs + tn * 32 + 8 * dq + 4 * i); }
;                 const float vn = vs[tn * 64 + e];
;                 const f32x2 v2 = (f32x2){ve, ve};
;                 f32x2 oa[2];
; #pragma unroll
;                 for (int i = 0; i < 2; ++i) {
;                     S[2 * i] = S[2 * i] * (f32x2){gg[i][0], gg[i][1]} + (f32x2){kk[i][0], kk[i][1]} * v2; S[2 * i + 1] = S[2 * i + 1] * (f32x2){gg[i][2], gg[i][3]} + (f32x2){kk[i][2], kk[i][3]} * v2;
;                     oa[i] = (f32x2){qq[i][0], qq[i][1]} * S[2 * i] + (f32x2){qq[i][2], qq[i][3]} * S[2 * i + 1];
;                 }
;                 const f32x2 os2 = oa[0] + oa[1];
;                 const float o = quad_sum(os2[0] + os2[1]);
;                 if (dq == 0) os[tok * 64 + e] = o;
; #pragma unroll
;                 for (int i = 0; i < 2; ++i) { kk[i] = kn[i]; qq[i] = qn[i]; gg[i] = gn[i]; }
;                 ve = vn;
	v_pk_mul_f32 v[116:117], v[8:9], v[36:37]
	v_pk_fma_f32 v[36:37], v[16:17], v[36:37], v[96:97]
	v_pk_mul_f32 v[118:119], v[10:11], v[34:35]
	v_pk_fma_f32 v[34:35], v[18:19], v[34:35], v[98:99]
	v_pk_fma_f32 v[116:117], v[12:13], v[32:33], v[116:117]
	v_pk_fma_f32 v[32:33], v[20:21], v[32:33], v[100:101]
	v_pk_fma_f32 v[118:119], v[14:15], v[30:31], v[118:119]
	v_pk_fma_f32 v[30:31], v[22:23], v[30:31], v[102:103]
	ds_read_b128 v[8:11], v120 offset:2688
	ds_read_b128 v[12:15], v120 offset:2704
	ds_read_b128 v[16:19], v120 offset:11008
	ds_read_b128 v[20:23], v120 offset:11024
	v_pk_add_f32 v[116:117], v[116:117], v[118:119]
	v_pk_mul_f32 v[104:105], v[114:115], v[88:89] op_sel_hi:[0,1]
	v_pk_mul_f32 v[106:107], v[114:115], v[90:91] op_sel_hi:[0,1]
	v_add_f32_e32 v116, v116, v117
	v_pk_mul_f32 v[108:109], v[114:115], v[92:93] op_sel_hi:[0,1]
	v_pk_mul_f32 v[110:111], v[114:115], v[94:95] op_sel_hi:[0,1]
	v_add_f32_dpp v116, v116, v116 quad_perm:[1,0,3,2] row_mask:0xf bank_mask:0xf bound_ctrl:1
	ds_read_b128 v[88:91], v120 offset:7040
	ds_read_b128 v[92:95], v120 offset:7056
	s_waitcnt lgkmcnt(11)
	ds_read_b32 v114, v121 offset:18176
	v_add_f32_dpp v116, v116, v116 quad_perm:[2,3,0,1] row_mask:0xf bank_mask:0xf bound_ctrl:1
	s_mov_b64 exec, s[38:39]
	ds_write_b32 v121, v116 offset:25344
	s_mov_b64 exec, s[0:1]
	s_waitcnt lgkmcnt(9)
	v_pk_mul_f32 v[116:117], v[0:1], v[36:37]
	v_pk_fma_f32 v[36:37], v[72:73], v[36:37], v[104:105]
	v_pk_mul_f32 v[118:119], v[2:3], v[34:35]
	v_pk_fma_f32 v[34:35], v[74:75], v[34:35], v[106:107]
	v_pk_fma_f32 v[116:117], v[4:5], v[32:33], v[116:117]
	v_pk_fma_f32 v[32:33], v[76:77], v[32:33], v[108:109]
	v_pk_fma_f32 v[118:119], v[6:7], v[30:31], v[118:119]
	v_pk_fma_f32 v[30:31], v[78:79], v[30:31], v[110:111]
	ds_read_b128 v[0:3], v120 offset:2816
	ds_read_b128 v[4:7], v120 offset:2832
	ds_read_b128 v[72:75], v120 offset:11136
	ds_read_b128 v[76:79], v120 offset:11152
	v_pk_add_f32 v[116:117], v[116:117], v[118:119]
	v_pk_mul_f32 v[96:97], v[112:113], v[80:81] op_sel_hi:[0,1]
	v_pk_mul_f32 v[98:99], v[112:113], v[82:83] op_sel_hi:[0,1]
	v_add_f32_e32 v116, v116, v117
	v_pk_mul_f32 v[100:101], v[112:113], v[84:85] op_sel_hi:[0,1]
	v_pk_mul_f32 v[102:103], v[112:113], v[86:87] op_sel_hi:[0,1]
	v_add_f32_dpp v116, v116, v116 quad_perm:[1,0,3,2] row_mask:0xf bank_mask:0xf bound_ctrl:1
	ds_read_b128 v[80:83], v120 offset:7168
	ds_read_b128 v[84:87], v120 offset:7184
	s_waitcnt lgkmcnt(11)
	ds_read_b32 v112, v121 offset:18432
	v_add_f32_dpp v116, v116, v116 quad_perm:[2,3,0,1] row_mask:0xf bank_mask:0xf bound_ctrl:1
	s_mov_b64 exec, s[38:39]
	ds_write_b32 v121, v116 offset:25600
	s_mov_b64 exec, s[0:1]
	s_waitcnt lgkmcnt(9)
	v_pk_mul_f32 v[116:117], v[8:9], v[36:37]
	v_pk_fma_f32 v[36:37], v[16:17], v[36:37], v[96:97]
	v_pk_mul_f32 v[118:119], v[10:11], v[34:35]
	v_pk_fma_f32 v[34:35], v[18:19], v[34:35], v[98:99]
	v_pk_fma_f32 v[116:117], v[12:13], v[32:33], v[116:117]
	v_pk_fma_f32 v[32:33], v[20:21], v[32:33], v[100:101]
	v_pk_fma_f32 v[118:119], v[14:15], v[30:31], v[118:119]
	v_pk_fma_f32 v[30:31], v[22:23], v[30:31], v[102:103]
	ds_read_b128 v[8:11], v120 offset:2944
	ds_read_b128 v[12:15], v120 offset:2960
	ds_read_b128 v[16:19], v120 offset:11264
	ds_read_b128 v[20:23], v120 offset:11280
	v_pk_add_f32 v[116:117], v[116:117], v[118:119]
	v_pk_mul_f32 v[104:105], v[114:115], v[88:89] op_sel_hi:[0,1]
	v_pk_mul_f32 v[106:107], v[114:115], v[90:91] op_sel_hi:[0,1]
	v_add_f32_e32 v116, v116, v117
	v_pk_mul_f32 v[108:109], v[114:115], v[92:93] op_sel_hi:[0,1]
	v_pk_mul_f32 v[110:111], v[114:115], v[94:95] op_sel_hi:[0,1]
	v_add_f32_dpp v116, v116, v116 quad_perm:[1,0,3,2] row_mask:0xf bank_mask:0xf bound_ctrl:1
	ds_read_b128 v[88:91], v120 offset:7296
	ds_read_b128 v[92:95], v120 offset:7312
	s_waitcnt lgkmcnt(11)
	ds_read_b32 v114, v121 offset:18688
	v_add_f32_dpp v116, v116, v116 quad_perm:[2,3,0,1] row_mask:0xf bank_mask:0xf bound_ctrl:1
	s_mov_b64 exec, s[38:39]
	ds_write_b32 v121, v116 offset:25856
	s_mov_b64 exec, s[0:1]
	s_waitcnt lgkmcnt(9)
	v_pk_mul_f32 v[116:117], v[0:1], v[36:37]
	v_pk_fma_f32 v[36:37], v[72:73], v[36:37], v[104:105]
	v_pk_mul_f32 v[118:119], v[2:3], v[34:35]
	v_pk_fma_f32 v[34:35], v[74:75], v[34:35], v[106:107]
	v_pk_fma_f32 v[116:117], v[4:5], v[32:33], v[116:117]
	v_pk_fma_f32 v[32:33], v[76:77], v[32:33], v[108:109]
	v_pk_fma_f32 v[118:119], v[6:7], v[30:31], v[118:119]
	v_pk_fma_f32 v[30:31], v[78:79], v[30:31], v[110:111]
	ds_read_b128 v[0:3], v120 offset:3072
	ds_read_b128 v[4:7], v120 offset:3088
	ds_read_b128 v[72:75], v120 offset:11392
	ds_read_b128 v[76:79], v120 offset:11408
	v_pk_add_f32 v[116:117], v[116:117], v[118:119]
	v_pk_mul_f32 v[96:97], v[112:113], v[80:81] op_sel_hi:[0,1]
	v_pk_mul_f32 v[98:99], v[112:113], v[82:83] op_sel_hi:[0,1]
	v_add_f32_e32 v116, v116, v117
	v_pk_mul_f32 v[100:101], v[112:113], v[84:85] op_sel_hi:[0,1]
	v_pk_mul_f32 v[102:103], v[112:113], v[86:87] op_sel_hi:[0,1]
	v_add_f32_dpp v116, v116, v116 quad_perm:[1,0,3,2] row_mask:0xf bank_mask:0xf bound_ctrl:1
	ds_read_b128 v[80:83], v120 offset:7424
	ds_read_b128 v[84:87], v120 offset:7440
	s_waitcnt lgkmcnt(11)
	ds_read_b32 v112, v121 offset:18944
	v_add_f32_dpp v116, v116, v116 quad_perm:[2,3,0,1] row_mask:0xf bank_mask:0xf bound_ctrl:1
	s_mov_b64 exec, s[38:39]
	ds_write_b32 v121, v116 offset:26112
	s_mov_b64 exec, s[0:1]
	s_waitcnt lgkmcnt(9)
; #define LAS __attribute__((address_space(3)))
; __device__ __forceinline__ float quad_sum(float v) { v += dppf<0xB1>(v); v += dppf<0x4E>(v); return v; }
; __device__ __forceinline__ void gla_unit(const Params& P, LAS unsigned char* lds, int li, bool sample, int b, int h, const int tid) {
;     ...
;             for (int tok = 0; tok < ntok; ++tok) {
;                 const int tn = min(tok + 1, ntok - 1);
;                 f32x4 kn[2], qn[2], gn[2];
; #pragma unroll
;                 for (int i = 0; i < 2; ++i) { kn[i] = *(const LAS f32x4*)(ks + tn * 32 + 8 * dq + 4 * i); qn[i] = *(const LAS f32x4*)(qs + tn * 32 + 8 * dq + 4 * i); gn[i] = *(const LAS f32x4*)(gs + tn * 32 + 8 * dq + 4 * i); }
;                 const float vn = vs[tn * 64 + e];
;                 const f32x2 v2 = (f32x2){ve, ve};
;                 f32x2 oa[2];
; #pragma unroll
;                 for (int i = 0; i < 2; ++i) {
;                     S[2 * i] = S[2 * i] * (f32x2){gg[i][0], gg[i][1]} + (f32x2){kk[i][0], kk[i][1]} * v2; S[2 * i + 1] = S[2 * i + 1] * (f32x2){gg[i][2], gg[i][3]} + (f32x2){kk[i][2], kk[i][3]} * v2;
;                     oa[i] = (f32x2){qq[i][0], qq[i][1]} * S[2 * i] + (f32x2){qq[i][2], qq[i][3]} * S[2 * i + 1];
;                 }
;                 const f32x2 os2 = oa[0] + oa[1];
;                 const float o = quad_sum(os2[0] + os2[1]);
;                 if (dq == 0) os[tok * 64 + e] = o;
; #pragma unroll
;                 for (int i = 0; i < 2; ++i) { kk[i] = kn[i]; qq[i] = qn[i]; gg[i] = gn[i]; }
;                 ve = vn;
	v_pk_mul_f32 v[116:117], v[8:9], v[36:37]
	v_pk_fma_f32 v[36:37], v[16:17], v[36:37], v[96:97]
	v_pk_mul_f32 v[118:119], v[10:11], v[34:35]
	v_pk_fma_f32 v[34:35], v[18:19], v[34:35], v[98:99]
	v_pk_fma_f32 v[116:117], v[12:13], v[32:33], v[116:117]
	v_pk_fma_f32 v[32:33], v[20:21], v[32:33], v[100:101]
	v_pk_fma_f32 v[118:119], v[14:15], v[30:31], v[118:119]
	v_pk_fma_f32 v[30:31], v[22:23], v[30:31], v[102:103]
	ds_read_b128 v[8:11], v120 offset:3200
	ds_read_b128 v[12:15], v120 offset:3216
	ds_read_b128 v[16:19], v120 offset:11520
	ds_read_b128 v[20:23], v120 offset:11536
	v_pk_add_f32 v[116:117], v[116:117], v[118:119]
	v_pk_mul_f32 v[104:105], v[114:115], v[88:89] op_sel_hi:[0,1]
	v_pk_mul_f32 v[106:107], v[114:115], v[90:91] op_sel_hi:[0,1]
	v_add_f32_e32 v116, v116, v117
	v_pk_mul_f32 v[108:109], v[114:115], v[92:93] op_sel_hi:[0,1]
	v_pk_mul_f32 v[110:111], v[114:115], v[94:95] op_sel_hi:[0,1]
	v_add_f32_dpp v116, v116, v116 quad_perm:[1,0,3,2] row_mask:0xf bank_mask:0xf bound_ctrl:1
	ds_read_b128 v[88:91], v120 offset:7552
	ds_read_b128 v[92:95], v120 offset:7568
	s_waitcnt lgkmcnt(11)
	ds_read_b32 v114, v121 offset:19200
	v_add_f32_dpp v116, v116, v116 quad_perm:[2,3,0,1] row_mask:0xf bank_mask:0xf bound_ctrl:1
	s_mov_b64 exec, s[38:39]
	ds_write_b32 v121, v116 offset:26368
	s_mov_b64 exec, s[0:1]
	s_waitcnt lgkmcnt(9)
	v_pk_mul_f32 v[116:117], v[0:1], v[36:37]
	v_pk_fma_f32 v[36:37], v[72:73], v[36:37], v[104:105]
	v_pk_mul_f32 v[118:119], v[2:3], v[34:35]
	v_pk_fma_f32 v[34:35], v[74:75], v[34:35], v[106:107]
	v_pk_fma_f32 v[116:117], v[4:5], v[32:33], v[116:117]
	v_pk_fma_f32 v[32:33], v[76:77], v[32:33], v[108:109]
	v_pk_fma_f32 v[118:119], v[6:7], v[30:31], v[118:119]
	v_pk_fma_f32 v[30:31], v[78:79], v[30:31], v[110:111]
	ds_read_b128 v[0:3], v120 offset:3328
	ds_read_b128 v[4:7], v120 offset:3344
	ds_read_b128 v[72:75], v120 offset:11648
	ds_read_b128 v[76:79], v120 offset:11664
	v_pk_add_f32 v[116:117], v[116:117], v[118:119]
	v_pk_mul_f32 v[96:97], v[112:113], v[80:81] op_sel_hi:[0,1]
	v_pk_mul_f32 v[98:99], v[112:113], v[82:83] op_sel_hi:[0,1]
	v_add_f32_e32 v116, v116, v117
	v_pk_mul_f32 v[100:101], v[112:113], v[84:85] op_sel_hi:[0,1]
	v_pk_mul_f32 v[102:103], v[112:113], v[86:87] op_sel_hi:[0,1]
	v_add_f32_dpp v116, v116, v116 quad_perm:[1,0,3,2] row_mask:0xf bank_mask:0xf bound_ctrl:1
	ds_read_b128 v[80:83], v120 offset:7680
	ds_read_b128 v[84:87], v120 offset:7696
	s_waitcnt lgkmcnt(11)
	ds_read_b32 v112, v121 offset:19456
	v_add_f32_dpp v116, v116, v116 quad_perm:[2,3,0,1] row_mask:0xf bank_mask:0xf bound_ctrl:1
	s_mov_b64 exec, s[38:39]
	ds_write_b32 v121, v116 offset:26624
	s_mov_b64 exec, s[0:1]
	s_waitcnt lgkmcnt(9)
	v_pk_mul_f32 v[116:117], v[8:9], v[36:37]
	v_pk_fma_f32 v[36:37], v[16:17], v[36:37], v[96:97]
	v_pk_mul_f32 v[118:119], v[10:11], v[34:35]
	v_pk_fma_f32 v[34:35], v[18:19], v[34:35], v[98:99]
	v_pk_fma_f32 v[116:117], v[12:13], v[32:33], v[116:117]
	v_pk_fma_f32 v[32:33], v[20:21], v[32:33], v[100:101]
	v_pk_fma_f32 v[118:119], v[14:15], v[30:31], v[118:119]
	v_pk_fma_f32 v[30:31], v[22:23], v[30:31], v[102:103]
	ds_read_b128 v[8:11], v120 offset:3456
	ds_read_b128 v[12:15], v120 offset:3472
	ds_read_b128 v[16:19], v120 offset:11776
	ds_read_b128 v[20:23], v120 offset:11792
	v_pk_add_f32 v[116:117], v[116:117], v[118:119]
	v_pk_mul_f32 v[104:105], v[114:115], v[88:89] op_sel_hi:[0,1]
	v_pk_mul_f32 v[106:107], v[114:115], v[90:91] op_sel_hi:[0,1]
	v_add_f32_e32 v116, v116, v117
	v_pk_mul_f32 v[108:109], v[114:115], v[92:93] op_sel_hi:[0,1]
	v_pk_mul_f32 v[110:111], v[114:115], v[94:95] op_sel_hi:[0,1]
	v_add_f32_dpp v116, v116, v116 quad_perm:[1,0,3,2] row_mask:0xf bank_mask:0xf bound_ctrl:1
	ds_read_b128 v[88:91], v120 offset:7808
	ds_read_b128 v[92:95], v120 offset:7824
	s_waitcnt lgkmcnt(11)
	ds_read_b32 v114, v121 offset:19712
	v_add_f32_dpp v116, v116, v116 quad_perm:[2,3,0,1] row_mask:0xf bank_mask:0xf bound_ctrl:1
	s_mov_b64 exec, s[38:39]
	ds_write_b32 v121, v116 offset:26880
	s_mov_b64 exec, s[0:1]
	s_waitcnt lgkmcnt(9)
	v_pk_mul_f32 v[116:117], v[0:1], v[36:37]
	v_pk_fma_f32 v[36:37], v[72:73], v[36:37], v[104:105]
	v_pk_mul_f32 v[118:119], v[2:3], v[34:35]
	v_pk_fma_f32 v[34:35], v[74:75], v[34:35], v[106:107]
	v_pk_fma_f32 v[116:117], v[4:5], v[32:33], v[116:117]
	v_pk_fma_f32 v[32:33], v[76:77], v[32:33], v[108:109]
	v_pk_fma_f32 v[118:119], v[6:7], v[30:31], v[118:119]
	v_pk_fma_f32 v[30:31], v[78:79], v[30:31], v[110:111]
	ds_read_b128 v[0:3], v120 offset:3584
	ds_read_b128 v[4:7], v120 offset:3600
	ds_read_b128 v[72:75], v120 offset:11904
	ds_read_b128 v[76:79], v120 offset:11920
	v_pk_add_f32 v[116:117], v[116:117], v[118:119]
	v_pk_mul_f32 v[96:97], v[112:113], v[80:81] op_sel_hi:[0,1]
	v_pk_mul_f32 v[98:99], v[112:113], v[82:83] op_sel_hi:[0,1]
	v_add_f32_e32 v116, v116, v117
	v_pk_mul_f32 v[100:101], v[112:113], v[84:85] op_sel_hi:[0,1]
	v_pk_mul_f32 v[102:103], v[112:113], v[86:87] op_sel_hi:[0,1]
	v_add_f32_dpp v116, v116, v116 quad_perm:[1,0,3,2] row_mask:0xf bank_mask:0xf bound_ctrl:1
	ds_read_b128 v[80:83], v120 offset:7936
	ds_read_b128 v[84:87], v120 offset:7952
	s_waitcnt lgkmcnt(11)
; #define LAS __attribute__((address_space(3)))
; __device__ __forceinline__ float quad_sum(float v) { v += dppf<0xB1>(v); v += dppf<0x4E>(v); return v; }
; __device__ __forceinline__ void gla_unit(const Params& P, LAS unsigned char* lds, int li, bool sample, int b, int h, const int tid) {
;     ...
;             for (int tok = 0; tok < ntok; ++tok) {
;                 const int tn = min(tok + 1, ntok - 1);
;                 f32x4 kn[2], qn[2], gn[2];
; #pragma unroll
;                 for (int i = 0; i < 2; ++i) { kn[i] = *(const LAS f32x4*)(ks + tn * 32 + 8 * dq + 4 * i); qn[i] = *(const LAS f32x4*)(qs + tn * 32 + 8 * dq + 4 * i); gn[i] = *(const LAS f32x4*)(gs + tn * 32 + 8 * dq + 4 * i); }
;                 const float vn = vs[tn * 64 + e];
;                 const f32x2 v2 = (f32x2){ve, ve};
;                 f32x2 oa[2];
; #pragma unroll
;                 for (int i = 0; i < 2; ++i) {
;                     S[2 * i] = S[2 * i] * (f32x2){gg[i][0], gg[i][1]} + (f32x2){kk[i][0], kk[i][1]} * v2; S[2 * i + 1] = S[2 * i + 1] * (f32x2){gg[i][2], gg[i][3]} + (f32x2){kk[i][2], kk[i][3]} * v2;
;                     oa[i] = (f32x2){qq[i][0], qq[i][1]} * S[2 * i] + (f32x2){qq[i][2], qq[i][3]} * S[2 * i + 1];
;                 }
;                 const f32x2 os2 = oa[0] + oa[1];
;                 const float o = quad_sum(os2[0] + os2[1]);
;                 if (dq == 0) os[tok * 64 + e] = o;
; #pragma unroll
;                 for (int i = 0; i < 2; ++i) { kk[i] = kn[i]; qq[i] = qn[i]; gg[i] = gn[i]; }
;                 ve = vn;
	ds_read_b32 v112, v121 offset:19968
	v_add_f32_dpp v116, v116, v116 quad_perm:[2,3,0,1] row_mask:0xf bank_mask:0xf bound_ctrl:1
	s_mov_b64 exec, s[38:39]
	ds_write_b32 v121, v116 offset:27136
	s_mov_b64 exec, s[0:1]
	s_waitcnt lgkmcnt(9)
	v_pk_mul_f32 v[116:117], v[8:9], v[36:37]
	v_pk_fma_f32 v[36:37], v[16:17], v[36:37], v[96:97]
	v_pk_mul_f32 v[118:119], v[10:11], v[34:35]
	v_pk_fma_f32 v[34:35], v[18:19], v[34:35], v[98:99]
	v_pk_fma_f32 v[116:117], v[12:13], v[32:33], v[116:117]
	v_pk_fma_f32 v[32:33], v[20:21], v[32:33], v[100:101]
	v_pk_fma_f32 v[118:119], v[14:15], v[30:31], v[118:119]
	v_pk_fma_f32 v[30:31], v[22:23], v[30:31], v[102:103]
	ds_read_b128 v[8:11], v120 offset:3712
	ds_read_b128 v[12:15], v120 offset:3728
	ds_read_b128 v[16:19], v120 offset:12032
	ds_read_b128 v[20:23], v120 offset:12048
	v_pk_add_f32 v[116:117], v[116:117], v[118:119]
	v_pk_mul_f32 v[104:105], v[114:115], v[88:89] op_sel_hi:[0,1]
	v_pk_mul_f32 v[106:107], v[114:115], v[90:91] op_sel_hi:[0,1]
	v_add_f32_e32 v116, v116, v117
	v_pk_mul_f32 v[108:109], v[114:115], v[92:93] op_sel_hi:[0,1]
	v_pk_mul_f32 v[110:111], v[114:115], v[94:95] op_sel_hi:[0,1]
	v_add_f32_dpp v116, v116, v116 quad_perm:[1,0,3,2] row_mask:0xf bank_mask:0xf bound_ctrl:1
	ds_read_b128 v[88:91], v120 offset:8064
	ds_read_b128 v[92:95], v120 offset:8080
	s_waitcnt lgkmcnt(11)
	ds_read_b32 v114, v121 offset:20224
	v_add_f32_dpp v116, v116, v116 quad_perm:[2,3,0,1] row_mask:0xf bank_mask:0xf bound_ctrl:1
	s_mov_b64 exec, s[38:39]
	ds_write_b32 v121, v116 offset:27392
	s_mov_b64 exec, s[0:1]
	s_waitcnt lgkmcnt(9)
	v_pk_mul_f32 v[116:117], v[0:1], v[36:37]
	v_pk_fma_f32 v[36:37], v[72:73], v[36:37], v[104:105]
	v_pk_mul_f32 v[118:119], v[2:3], v[34:35]
	v_pk_fma_f32 v[34:35], v[74:75], v[34:35], v[106:107]
	v_pk_fma_f32 v[116:117], v[4:5], v[32:33], v[116:117]
	v_pk_fma_f32 v[32:33], v[76:77], v[32:33], v[108:109]
	v_pk_fma_f32 v[118:119], v[6:7], v[30:31], v[118:119]
	v_pk_fma_f32 v[30:31], v[78:79], v[30:31], v[110:111]
	ds_read_b128 v[0:3], v120 offset:3840
	ds_read_b128 v[4:7], v120 offset:3856
	ds_read_b128 v[72:75], v120 offset:12160
	ds_read_b128 v[76:79], v120 offset:12176
	v_pk_add_f32 v[116:117], v[116:117], v[118:119]
	v_pk_mul_f32 v[96:97], v[112:113], v[80:81] op_sel_hi:[0,1]
	v_pk_mul_f32 v[98:99], v[112:113], v[82:83] op_sel_hi:[0,1]
	v_add_f32_e32 v116, v116, v117
	v_pk_mul_f32 v[100:101], v[112:113], v[84:85] op_sel_hi:[0,1]
	v_pk_mul_f32 v[102:103], v[112:113], v[86:87] op_sel_hi:[0,1]
	v_add_f32_dpp v116, v116, v116 quad_perm:[1,0,3,2] row_mask:0xf bank_mask:0xf bound_ctrl:1
	s_nop 1
	v_add_f32_dpp v116, v116, v116 quad_perm:[2,3,0,1] row_mask:0xf bank_mask:0xf bound_ctrl:1
	s_mov_b64 exec, s[38:39]
	ds_write_b32 v121, v116 offset:27648
	s_mov_b64 exec, s[0:1]
	s_waitcnt lgkmcnt(6)
	v_pk_mul_f32 v[116:117], v[8:9], v[36:37]
	v_pk_fma_f32 v[36:37], v[16:17], v[36:37], v[96:97]
	v_pk_mul_f32 v[118:119], v[10:11], v[34:35]
	v_pk_fma_f32 v[34:35], v[18:19], v[34:35], v[98:99]
	v_pk_fma_f32 v[116:117], v[12:13], v[32:33], v[116:117]
	v_pk_fma_f32 v[32:33], v[20:21], v[32:33], v[100:101]
	v_pk_fma_f32 v[118:119], v[14:15], v[30:31], v[118:119]
	v_pk_fma_f32 v[30:31], v[22:23], v[30:31], v[102:103]
	ds_read_b128 v[8:11], v120 offset:3968
	ds_read_b128 v[12:15], v120 offset:3984
	v_pk_add_f32 v[116:117], v[116:117], v[118:119]
	v_pk_mul_f32 v[104:105], v[114:115], v[88:89] op_sel_hi:[0,1]
	v_pk_mul_f32 v[106:107], v[114:115], v[90:91] op_sel_hi:[0,1]
	v_add_f32_e32 v116, v116, v117
	v_pk_mul_f32 v[108:109], v[114:115], v[92:93] op_sel_hi:[0,1]
	v_pk_mul_f32 v[110:111], v[114:115], v[94:95] op_sel_hi:[0,1]
	v_add_f32_dpp v116, v116, v116 quad_perm:[1,0,3,2] row_mask:0xf bank_mask:0xf bound_ctrl:1
	s_nop 1
	v_add_f32_dpp v116, v116, v116 quad_perm:[2,3,0,1] row_mask:0xf bank_mask:0xf bound_ctrl:1
	s_mov_b64 exec, s[38:39]
	ds_write_b32 v121, v116 offset:27904
	s_mov_b64 exec, s[0:1]
	s_waitcnt lgkmcnt(4)
	v_pk_mul_f32 v[116:117], v[0:1], v[36:37]
	v_pk_fma_f32 v[36:37], v[72:73], v[36:37], v[104:105]
	v_pk_mul_f32 v[118:119], v[2:3], v[34:35]
	v_pk_fma_f32 v[34:35], v[74:75], v[34:35], v[106:107]
	v_pk_fma_f32 v[116:117], v[4:5], v[32:33], v[116:117]
	v_pk_fma_f32 v[32:33], v[76:77], v[32:33], v[108:109]
	v_pk_fma_f32 v[118:119], v[6:7], v[30:31], v[118:119]
	v_pk_fma_f32 v[30:31], v[78:79], v[30:31], v[110:111]
	v_pk_add_f32 v[116:117], v[116:117], v[118:119]
	v_add_f32_e32 v116, v116, v117
	s_nop 1
	v_add_f32_dpp v116, v116, v116 quad_perm:[1,0,3,2] row_mask:0xf bank_mask:0xf bound_ctrl:1
	s_nop 1
	v_add_f32_dpp v116, v116, v116 quad_perm:[2,3,0,1] row_mask:0xf bank_mask:0xf bound_ctrl:1
	s_mov_b64 exec, s[38:39]
	ds_write_b32 v121, v116 offset:28160
	s_mov_b64 exec, s[0:1]
	s_waitcnt lgkmcnt(2)
	v_pk_mul_f32 v[116:117], v[8:9], v[36:37]
	v_pk_mul_f32 v[118:119], v[10:11], v[34:35]
	v_pk_fma_f32 v[116:117], v[12:13], v[32:33], v[116:117]
	v_pk_fma_f32 v[118:119], v[14:15], v[30:31], v[118:119]
	v_pk_add_f32 v[116:117], v[116:117], v[118:119]
	v_add_f32_e32 v116, v116, v117
	s_nop 1
	v_add_f32_dpp v116, v116, v116 quad_perm:[1,0,3,2] row_mask:0xf bank_mask:0xf bound_ctrl:1
	s_nop 1
	v_add_f32_dpp v116, v116, v116 quad_perm:[2,3,0,1] row_mask:0xf bank_mask:0xf bound_ctrl:1
	s_mov_b64 exec, s[38:39]
	ds_write_b32 v121, v116 offset:28416
	s_mov_b64 exec, s[0:1]

; __device__ __forceinline__ void gla_unit(const Params& P, LAS unsigned char* lds, int li, bool sample, int b, int h, const int tid) {
;     ...
;     for (int j = 0; j < NC + 2; ++j) {
;         if (wid >= 4) {
;             if (j < NC) {
;                 LAS float* qs = (LAS float*)(lds + (j & 1) * SET); LAS float* ks = qs + 1024; LAS float* gs = qs + 2048; LAS float* vs = qs + 3072;
;                 const int t0 = j * MX_CH + pw * 8;
;                 if (t0 < L) {
;                     const int g4 = (lane >> 5) * 4;
;                     float rv[8], rq[4], rk[4]; f32x4 lrv[4][4];
; #pragma unroll
;                     for (int i = 0; i < 8; ++i) rv[i] = bf2f(PROJ[(size_t)(rowbase + t0 + i) * ABIN + 2576 + h * 64 + c]);
; #pragma unroll
;                     for (int i = 0; i < 4; ++i) { const size_t row = (size_t)(rowbase + t0 + g4 + i); const bf16_t* pr = PROJ + row * ABIN;
;                         rq[i] = bf2f(pr[2064 + h * 32 + c32]); rk[i] = bf2f(pr[2320 + h * 32 + c32]);
; #pragma unroll
;                         for (int r = 0; r < 4; ++r) lrv[i][r] = *(const f32x4*)(GATES + row * 32 + 16 + 4 * r); }
; #pragma unroll
;                     for (int i = 0; i < 8; ++i) vs[(pw * 8 + i) * 64 + c] = rv[i];
; #pragma unroll
;                     for (int i = 0; i < 4; ++i) {
;                         const int tok = pw * 8 + g4 + i;
;                         float z = gkb;
; #pragma unroll
;                         for (int r = 0; r < 4; ++r) z += (lrv[i][r][0] * w2[4 * r] + lrv[i][r][1] * w2[4 * r + 1]) + (lrv[i][r][2] * w2[4 * r + 2] + lrv[i][r][3] * w2[4 * r + 3]);
;                         const float ls = -softplus_f(-z);
;                         qs[tok * 32 + c32] = rq[i] * 0.17677669529663687f; ks[tok * 32 + c32] = rk[i]; gs[tok * 32 + c32] = __expf(ls * (1.0f / 16.0f));
;                     }
;                 }
;             }
;             if (j >= 2) {
;                 LAS float* os = (LAS float*)(lds + (j & 1) * SET) + 3072 + 2048;
;                 const int t0 = (j - 2) * MX_CH + pw * 8;
;                 if (t0 < L) {
; #pragma unroll
;                     for (int i = 0; i < 8; ++i) {
;                         const int tok = pw * 8 + i; const size_t row = (size_t)(rowbase + t0 + i);
;                         MIX[row * DM + 512 + h * 64 + c] = (bf16_t)f2bf(os[tok * 64 + c]);
;                     }
;                 }
;             }
.LBB0_287:
	s_andn2_b64 vcc, exec, s[56:57]
	s_cbranch_vccnz .LBB0_552
	s_mov_b64 s[0:1], -1
	s_lshr_b32 s11, s69, 5
	s_lshr_b32 s16, s69, 1
	s_andn2_b64 vcc, exec, s[18:19]
	v_and_b32_e32 v165, 15, v166
	s_waitcnt lgkmcnt(0)
	s_barrier
	s_cbranch_vccz .LBB0_438
	s_xor_b64 s[12:13], s[28:29], -1
	s_lshr_b32 s49, s69, 3
	s_lshr_b32 s96, s48, 3
	s_cmp_lt_i32 s94, s49
	s_cselect_b64 s[0:1], -1, 0
	s_cmp_ge_i32 s94, s49
	v_or_b32_e32 v167, 0x8000, v165
	s_cselect_b64 s[56:57], -1, 0
	s_mov_b64 s[18:19], -1
	s_and_b64 vcc, exec, s[12:13]
	s_cbranch_vccz .LBB0_369
	s_xor_b64 s[12:13], s[82:83], -1
	s_and_b64 vcc, exec, s[12:13]
	s_cbranch_vccz .LBB0_319
	s_andn2_b64 vcc, exec, s[0:1]
	s_cbranch_vccnz .LBB0_298
	s_mul_i32 s12, s96, s61
	s_waitcnt vmcnt(16)
	v_mul_u32_u24_e64 v1, s48, 48
	s_ashr_i32 s13, s12, 31
	s_lshl_b32 s2, s61, 12
	v_lshrrev_b32_e32 v0, 2, v164
	s_waitcnt vmcnt(12)
	v_lshlrev_b32_e32 v2, 1, v1
	v_mov_b32_e32 v3, v161
	s_cmp_lt_u32 s76, 64
	v_and_b32_e32 v0, 12, v0
	v_and_b32_e32 v160, 48, v166
	v_lshl_add_u64 v[2:3], s[62:63], 0, v[2:3]
	v_lshl_add_u32 v42, v164, 4, 0
	s_cselect_b64 s[0:1], -1, 0
	s_lshl_b64 s[18:19], s[12:13], 1
	s_waitcnt vmcnt(3)
	v_lshl_add_u64 v[18:19], s[70:71], 0, v[160:161]
	s_lshl_b32 s4, s48, 1
	s_waitcnt vmcnt(0)
	v_lshl_add_u64 v[20:21], s[62:63], 0, v[160:161]
	v_lshl_add_u64 v[22:23], v[2:3], 0, v[160:161]
	v_lshlrev_b32_e32 v24, 1, v0
	s_mov_b32 s12, s94
	s_branch .LBB0_294
	s_nop 0
	s_nop 0
	s_nop 0
	s_nop 0
	s_nop 0
	s_nop 0
	s_nop 0
	s_nop 0
	s_nop 0
	s_nop 0
	s_nop 0
	s_nop 0
	s_nop 0
	s_nop 0
	s_nop 0
